# P5/P6 K-loop load segments: LDS-DMA stage issue hoisted above the fragment ds_reads (longer DMA flight time)
# speedup vs baseline: 1.0207x; 1.0207x over previous
; #define PG8_LDA(dst, b, h) do { if constexpr (FP8) { _Pragma("unroll") for (int m = 0; m < 4; ++m) dst##8[m] = PG8_LD8(PG8_SA(b, h), aoff, aoff1, m); } \
;         else { _Pragma("unroll") for (int m = 0; m < 4; ++m) _Pragma("unroll") for (int k = 0; k < 2; ++k) dst[m][k] = *(const LAS bf16x8*)(lds + PG8_SA(b, h) + (k ? aoff1 : aoff) + m * 2048); } } while (0)
; #define PG8_LDB(dst, b, h) do { if constexpr (FP8) { dst##8[0] = PG8_LD8(PG8_SB(b, h), boff, boff1, 0); dst##8[1] = PG8_LD8(PG8_SB(b, h), boff, boff1, 1); } \
;         else { _Pragma("unroll") for (int n = 0; n < 2; ++n) _Pragma("unroll") for (int k = 0; k < 2; ++k) dst[n][k] = *(const LAS bf16x8*)(lds + PG8_SB(b, h) + (k ? boff1 : boff) + n * 2048); } } while (0)
; #define PG8_WAIT_V(n) asm volatile("s_waitcnt vmcnt(" #n ")" ::: "memory")
; #define PG8_WAIT_L(n) asm volatile("s_waitcnt lgkmcnt(" #n ")" ::: "memory")
; #define PG8_BAR __builtin_amdgcn_s_barrier()
; #define PG8_SCHED __builtin_amdgcn_sched_barrier(0)
; #define PG8_S1 PG8_STAGE(PG8_SA(1, 1), a1 + hstepA, voffA)
; #define PG8_S2 do { PG8_STAGE(PG8_SB(0, 0), b2, voffB); PG8_STAGE(PG8_SB(0, 1), b2 + hstepB, voffB); PG8_STAGE(PG8_SA(0, 0), a2, voffA); } while (0)
; template <class Epi, class SchedT, bool ALIGN_EPI, bool SP2, bool FP8 = false>
; __device__ __forceinline__ void gemm_phase(LAS unsigned char* lds, const Gemm g, const SchedT& S, const Epi& E, const int wid) {
;     ...
;             const bool last = (t == nt - 2);
;             const char* a1 = cA + (size_t)(t + 1) * kstep;
;             const char* a2 = last ? nA : cA + (size_t)(t + 2) * kstep; const char* b2 = last ? nB : cB + (size_t)(t + 2) * kstep;
;             const char* a3 = a2 + kstep; const char* b3 = b2 + kstep;
;             if constexpr (SP2) {
;     ...
;             PG8_LDB(B0, 0, 0); PG8_LDB(B1, 0, 1); PG8_SCHED; PG8_LDA(At, 0, 0); PG8_S1;
;             PG8_WAIT_V(8); PG8_WAIT_L(0); PG8_BAR; PG8_MMAP(0, 0, 0); PG8_BAR; PG8_SCHED;
;             PG8_LDA(At, 0, 1); PG8_S2;
;             PG8_WAIT_V(8); PG8_WAIT_L(0); PG8_BAR; PG8_MMAP(1, 0, 1); PG8_BAR; PG8_SCHED;
.LBB0_899:
	s_add_i32 s35, s34, 2
	s_add_u32 s16, s48, 0xfffc0080
	s_addc_u32 s17, s49, -1
	s_cmp_eq_u32 s27, s34
	s_cselect_b32 s51, s15, s17
	s_cselect_b32 s50, s21, s16
	s_cselect_b32 s53, s24, s31
	s_cselect_b32 s52, s25, s30
	v_mov_b32_e32 v144, v168
	s_add_i32 m0, s87, 0xc000
	s_nop 0
	global_load_lds_dwordx4 v144, s[48:49]
	v_mov_b32_e32 v144, v170
	s_add_i32 m0, s87, 0xe000
	s_nop 0
	global_load_lds_dwordx4 v144, s[48:49]
	ds_read_b128 v[128:131], v173
	ds_read_b128 v[132:135], v173 offset:1024
	ds_read_b128 v[136:139], v174
	ds_read_b128 v[140:143], v174 offset:1024
	ds_read_b128 v[150:153], v175
	ds_read_b128 v[154:157], v175 offset:1024
	ds_read_b128 v[158:161], v176
	ds_read_b128 v[162:165], v176 offset:1024
	ds_read_b128 v[182:185], v177
	ds_read_b128 v[186:189], v177 offset:1024
	ds_read_b128 v[190:193], v177 offset:2048
	ds_read_b128 v[194:197], v177 offset:3072
	ds_read_b128 v[198:201], v177 offset:4096
	ds_read_b128 v[202:205], v177 offset:5120
	ds_read_b128 v[206:209], v177 offset:6144
	ds_read_b128 v[210:213], v177 offset:7168
	s_waitcnt vmcnt(8)
	s_waitcnt lgkmcnt(0)
	s_barrier
	s_setprio 1
	s_waitcnt lgkmcnt(0)
	v_mfma_f32_16x16x32_bf16 v[124:127], v[128:131], v[182:185], v[124:127]
	v_mfma_f32_16x16x32_bf16 v[120:123], v[136:139], v[182:185], v[120:123]
	v_mfma_f32_16x16x32_bf16 v[108:111], v[128:131], v[190:193], v[108:111]
	v_mfma_f32_16x16x32_bf16 v[104:107], v[136:139], v[190:193], v[104:107]
	v_mfma_f32_16x16x32_bf16 v[92:95], v[128:131], v[198:201], v[92:95]
	v_mfma_f32_16x16x32_bf16 v[88:91], v[136:139], v[198:201], v[88:91]
	v_mfma_f32_16x16x32_bf16 v[76:79], v[128:131], v[206:209], v[76:79]
	v_mfma_f32_16x16x32_bf16 v[72:75], v[136:139], v[206:209], v[72:75]
	v_mfma_f32_16x16x32_bf16 v[124:127], v[132:135], v[186:189], v[124:127]
	v_mfma_f32_16x16x32_bf16 v[120:123], v[140:143], v[186:189], v[120:123]
	v_mfma_f32_16x16x32_bf16 v[108:111], v[132:135], v[194:197], v[108:111]
	v_mfma_f32_16x16x32_bf16 v[104:107], v[140:143], v[194:197], v[104:107]
	v_mfma_f32_16x16x32_bf16 v[92:95], v[132:135], v[202:205], v[92:95]
	v_mfma_f32_16x16x32_bf16 v[88:91], v[140:143], v[202:205], v[88:91]
	v_mfma_f32_16x16x32_bf16 v[76:79], v[132:135], v[210:213], v[76:79]
	v_mfma_f32_16x16x32_bf16 v[72:75], v[140:143], v[210:213], v[72:75]
	s_setprio 0
	s_setprio 1
	v_mfma_f32_16x16x32_bf16 v[116:119], v[150:153], v[182:185], v[116:119]
	v_mfma_f32_16x16x32_bf16 v[112:115], v[158:161], v[182:185], v[112:115]
	v_mfma_f32_16x16x32_bf16 v[100:103], v[150:153], v[190:193], v[100:103]
	v_mfma_f32_16x16x32_bf16 v[96:99], v[158:161], v[190:193], v[96:99]
	v_mfma_f32_16x16x32_bf16 v[84:87], v[150:153], v[198:201], v[84:87]
	v_mfma_f32_16x16x32_bf16 v[80:83], v[158:161], v[198:201], v[80:83]
	v_mfma_f32_16x16x32_bf16 v[68:71], v[150:153], v[206:209], v[68:71]
	v_mfma_f32_16x16x32_bf16 v[64:67], v[158:161], v[206:209], v[64:67]
	v_mfma_f32_16x16x32_bf16 v[116:119], v[154:157], v[186:189], v[116:119]
	v_mfma_f32_16x16x32_bf16 v[112:115], v[162:165], v[186:189], v[112:115]
	v_mfma_f32_16x16x32_bf16 v[100:103], v[154:157], v[194:197], v[100:103]
	v_mfma_f32_16x16x32_bf16 v[96:99], v[162:165], v[194:197], v[96:99]
	v_mfma_f32_16x16x32_bf16 v[84:87], v[154:157], v[202:205], v[84:87]
	v_mfma_f32_16x16x32_bf16 v[80:83], v[162:165], v[202:205], v[80:83]
	v_mfma_f32_16x16x32_bf16 v[68:71], v[154:157], v[210:213], v[68:71]
	v_mfma_f32_16x16x32_bf16 v[64:67], v[162:165], v[210:213], v[64:67]
	s_setprio 0
	s_barrier
	v_mov_b32_e32 v144, v169
	s_add_i32 s16, s94, s86
	s_mov_b32 m0, s16
	s_nop 0
	global_load_lds_dwordx4 v144, s[52:53]
	v_mov_b32_e32 v144, v171
	s_add_i32 m0, s16, 0x2000
	s_add_u32 s60, s52, 0x40000
	global_load_lds_dwordx4 v144, s[52:53]
	s_addc_u32 s61, s53, 0
	v_mov_b32_e32 v144, v169
	s_add_i32 s16, s95, s86
	s_mov_b32 m0, s16
	s_nop 0
	global_load_lds_dwordx4 v144, s[60:61]
	v_mov_b32_e32 v144, v171
	s_add_i32 m0, s16, 0x2000
	s_nop 0
	global_load_lds_dwordx4 v144, s[60:61]
	v_mov_b32_e32 v144, v168
	s_mov_b32 m0, s87
	s_nop 0
	global_load_lds_dwordx4 v144, s[50:51]
	v_mov_b32_e32 v144, v170
	s_mov_b32 m0, s88
	s_nop 0
	global_load_lds_dwordx4 v144, s[50:51]
	ds_read_b128 v[182:185], v177 offset:16384
	ds_read_b128 v[186:189], v177 offset:17408
	ds_read_b128 v[190:193], v177 offset:18432
	ds_read_b128 v[194:197], v177 offset:19456
	ds_read_b128 v[198:201], v177 offset:20480
	ds_read_b128 v[202:205], v177 offset:21504
	ds_read_b128 v[206:209], v177 offset:22528
	ds_read_b128 v[210:213], v177 offset:23552
	s_waitcnt vmcnt(8)
	s_waitcnt lgkmcnt(0)
	s_barrier
; #define PG8_LDA(dst, b, h) do { if constexpr (FP8) { _Pragma("unroll") for (int m = 0; m < 4; ++m) dst##8[m] = PG8_LD8(PG8_SA(b, h), aoff, aoff1, m); } \
;         else { _Pragma("unroll") for (int m = 0; m < 4; ++m) _Pragma("unroll") for (int k = 0; k < 2; ++k) dst[m][k] = *(const LAS bf16x8*)(lds + PG8_SA(b, h) + (k ? aoff1 : aoff) + m * 2048); } } while (0)
; #define PG8_LDB(dst, b, h) do { if constexpr (FP8) { dst##8[0] = PG8_LD8(PG8_SB(b, h), boff, boff1, 0); dst##8[1] = PG8_LD8(PG8_SB(b, h), boff, boff1, 1); } \
;         else { _Pragma("unroll") for (int n = 0; n < 2; ++n) _Pragma("unroll") for (int k = 0; k < 2; ++k) dst[n][k] = *(const LAS bf16x8*)(lds + PG8_SB(b, h) + (k ? boff1 : boff) + n * 2048); } } while (0)
; #define PG8_WAIT_V(n) asm volatile("s_waitcnt vmcnt(" #n ")" ::: "memory")
; #define PG8_WAIT_L(n) asm volatile("s_waitcnt lgkmcnt(" #n ")" ::: "memory")
; #define PG8_BAR __builtin_amdgcn_s_barrier()
; #define PG8_SCHED __builtin_amdgcn_sched_barrier(0)
; #define PG8_S1 PG8_STAGE(PG8_SA(1, 1), a1 + hstepA, voffA)
; #define PG8_S2 do { PG8_STAGE(PG8_SB(0, 0), b2, voffB); PG8_STAGE(PG8_SB(0, 1), b2 + hstepB, voffB); PG8_STAGE(PG8_SA(0, 0), a2, voffA); } while (0)
; #define PG8_S3 PG8_STAGE(PG8_SA(0, 1), a2 + hstepA, voffA)
; #define PG8_S4 do { PG8_STAGE(PG8_SB(1, 0), b3, voffB); PG8_STAGE(PG8_SB(1, 1), b3 + hstepB, voffB); PG8_STAGE(PG8_SA(1, 0), a3, voffA); } while (0)
; template <class Epi, class SchedT, bool ALIGN_EPI, bool SP2, bool FP8 = false>
; __device__ __forceinline__ void gemm_phase(LAS unsigned char* lds, const Gemm g, const SchedT& S, const Epi& E, const int wid) {
;     ...
;             PG8_LDB(B0, 0, 0); PG8_LDB(B1, 0, 1); PG8_SCHED; PG8_LDA(At, 0, 0); PG8_S1;
;             PG8_WAIT_V(8); PG8_WAIT_L(0); PG8_BAR; PG8_MMAP(0, 0, 0); PG8_BAR; PG8_SCHED;
;             PG8_LDA(At, 0, 1); PG8_S2;
;             PG8_WAIT_V(8); PG8_WAIT_L(0); PG8_BAR; PG8_MMAP(1, 0, 1); PG8_BAR; PG8_SCHED;
;             PG8_LDB(B0, 1, 0); PG8_LDB(B1, 1, 1); PG8_SCHED; PG8_LDA(At, 1, 0); PG8_S3;
;             PG8_WAIT_V(8); PG8_WAIT_L(0); PG8_BAR; PG8_MMAP(0, 1, 0); PG8_BAR; PG8_SCHED;
;             PG8_LDA(At, 1, 1); PG8_S4;
;             PG8_WAIT_V(8); PG8_WAIT_L(0); PG8_BAR; PG8_MMAP(1, 1, 1); PG8_BAR; PG8_SCHED;
	s_setprio 1
	s_waitcnt lgkmcnt(0)
	v_mfma_f32_16x16x32_bf16 v[60:63], v[128:131], v[182:185], v[60:63]
	v_mfma_f32_16x16x32_bf16 v[56:59], v[136:139], v[182:185], v[56:59]
	v_mfma_f32_16x16x32_bf16 v[44:47], v[128:131], v[190:193], v[44:47]
	v_mfma_f32_16x16x32_bf16 v[40:43], v[136:139], v[190:193], v[40:43]
	v_mfma_f32_16x16x32_bf16 v[28:31], v[128:131], v[198:201], v[28:31]
	v_mfma_f32_16x16x32_bf16 v[24:27], v[136:139], v[198:201], v[24:27]
	v_mfma_f32_16x16x32_bf16 v[12:15], v[128:131], v[206:209], v[12:15]
	v_mfma_f32_16x16x32_bf16 v[8:11], v[136:139], v[206:209], v[8:11]
	v_mfma_f32_16x16x32_bf16 v[60:63], v[132:135], v[186:189], v[60:63]
	v_mfma_f32_16x16x32_bf16 v[56:59], v[140:143], v[186:189], v[56:59]
	v_mfma_f32_16x16x32_bf16 v[44:47], v[132:135], v[194:197], v[44:47]
	v_mfma_f32_16x16x32_bf16 v[40:43], v[140:143], v[194:197], v[40:43]
	v_mfma_f32_16x16x32_bf16 v[28:31], v[132:135], v[202:205], v[28:31]
	v_mfma_f32_16x16x32_bf16 v[24:27], v[140:143], v[202:205], v[24:27]
	v_mfma_f32_16x16x32_bf16 v[12:15], v[132:135], v[210:213], v[12:15]
	v_mfma_f32_16x16x32_bf16 v[8:11], v[140:143], v[210:213], v[8:11]
	s_setprio 0
	s_setprio 1
	v_mfma_f32_16x16x32_bf16 v[52:55], v[150:153], v[182:185], v[52:55]
	v_mfma_f32_16x16x32_bf16 v[48:51], v[158:161], v[182:185], v[48:51]
	v_mfma_f32_16x16x32_bf16 v[36:39], v[150:153], v[190:193], v[36:39]
	v_mfma_f32_16x16x32_bf16 v[32:35], v[158:161], v[190:193], v[32:35]
	v_mfma_f32_16x16x32_bf16 v[20:23], v[150:153], v[198:201], v[20:23]
	v_mfma_f32_16x16x32_bf16 v[16:19], v[158:161], v[198:201], v[16:19]
	v_mfma_f32_16x16x32_bf16 v[4:7], v[150:153], v[206:209], v[4:7]
	v_mfma_f32_16x16x32_bf16 v[0:3], v[158:161], v[206:209], v[0:3]
	v_mfma_f32_16x16x32_bf16 v[52:55], v[154:157], v[186:189], v[52:55]
	v_mfma_f32_16x16x32_bf16 v[48:51], v[162:165], v[186:189], v[48:51]
	v_mfma_f32_16x16x32_bf16 v[36:39], v[154:157], v[194:197], v[36:39]
	v_mfma_f32_16x16x32_bf16 v[32:35], v[162:165], v[194:197], v[32:35]
	v_mfma_f32_16x16x32_bf16 v[20:23], v[154:157], v[202:205], v[20:23]
	v_mfma_f32_16x16x32_bf16 v[16:19], v[162:165], v[202:205], v[16:19]
	v_mfma_f32_16x16x32_bf16 v[4:7], v[154:157], v[210:213], v[4:7]
	v_mfma_f32_16x16x32_bf16 v[0:3], v[162:165], v[210:213], v[0:3]
	s_setprio 0
	s_barrier
	s_add_i32 s16, 0, 0x18000
	s_add_i32 s17, 0, 0x1c000
	s_add_u32 s60, s50, 0x40000
	s_mov_b32 m0, s89
	s_addc_u32 s61, s51, 0
	s_nop 0
	global_load_lds_dwordx4 v168, s[60:61]
	s_mov_b32 m0, s90
	s_nop 0
	global_load_lds_dwordx4 v170, s[60:61]
	v_add_u32_e32 v132, s16, v172
	v_add_u32_e32 v144, s17, v172
	ds_read_b128 v[128:131], v132
	ds_read_b128 v[132:135], v132 offset:1024
	ds_read_b128 v[136:139], v178
	ds_read_b128 v[140:143], v178 offset:1024
	ds_read_b128 v[150:153], v144
	ds_read_b128 v[154:157], v144 offset:1024
	ds_read_b128 v[158:161], v179
	ds_read_b128 v[162:165], v179 offset:1024
	ds_read_b128 v[182:185], v177 offset:32768
	ds_read_b128 v[186:189], v177 offset:33792
	ds_read_b128 v[190:193], v177 offset:34816
	ds_read_b128 v[194:197], v177 offset:35840
	ds_read_b128 v[198:201], v177 offset:36864
	ds_read_b128 v[202:205], v177 offset:37888
	ds_read_b128 v[206:209], v177 offset:38912
	ds_read_b128 v[210:213], v177 offset:39936
	s_waitcnt vmcnt(8)
	s_waitcnt lgkmcnt(0)
	s_barrier
	s_setprio 1
	s_waitcnt lgkmcnt(0)
	v_mfma_f32_16x16x32_bf16 v[124:127], v[128:131], v[182:185], v[124:127]
	v_mfma_f32_16x16x32_bf16 v[120:123], v[136:139], v[182:185], v[120:123]
	v_mfma_f32_16x16x32_bf16 v[108:111], v[128:131], v[190:193], v[108:111]
	v_mfma_f32_16x16x32_bf16 v[104:107], v[136:139], v[190:193], v[104:107]
	v_mfma_f32_16x16x32_bf16 v[92:95], v[128:131], v[198:201], v[92:95]
	v_mfma_f32_16x16x32_bf16 v[88:91], v[136:139], v[198:201], v[88:91]
	v_mfma_f32_16x16x32_bf16 v[76:79], v[128:131], v[206:209], v[76:79]
	v_mfma_f32_16x16x32_bf16 v[72:75], v[136:139], v[206:209], v[72:75]
	v_mfma_f32_16x16x32_bf16 v[124:127], v[132:135], v[186:189], v[124:127]
	v_mfma_f32_16x16x32_bf16 v[120:123], v[140:143], v[186:189], v[120:123]
	v_mfma_f32_16x16x32_bf16 v[108:111], v[132:135], v[194:197], v[108:111]
	v_mfma_f32_16x16x32_bf16 v[104:107], v[140:143], v[194:197], v[104:107]
	v_mfma_f32_16x16x32_bf16 v[92:95], v[132:135], v[202:205], v[92:95]
	v_mfma_f32_16x16x32_bf16 v[88:91], v[140:143], v[202:205], v[88:91]
	v_mfma_f32_16x16x32_bf16 v[76:79], v[132:135], v[210:213], v[76:79]
	v_mfma_f32_16x16x32_bf16 v[72:75], v[140:143], v[210:213], v[72:75]
	s_setprio 0
	s_setprio 1
	v_mfma_f32_16x16x32_bf16 v[116:119], v[150:153], v[182:185], v[116:119]
	v_mfma_f32_16x16x32_bf16 v[112:115], v[158:161], v[182:185], v[112:115]
	v_mfma_f32_16x16x32_bf16 v[100:103], v[150:153], v[190:193], v[100:103]
	v_mfma_f32_16x16x32_bf16 v[96:99], v[158:161], v[190:193], v[96:99]
	v_mfma_f32_16x16x32_bf16 v[84:87], v[150:153], v[198:201], v[84:87]
	v_mfma_f32_16x16x32_bf16 v[80:83], v[158:161], v[198:201], v[80:83]
	v_mfma_f32_16x16x32_bf16 v[68:71], v[150:153], v[206:209], v[68:71]
	v_mfma_f32_16x16x32_bf16 v[64:67], v[158:161], v[206:209], v[64:67]
	v_mfma_f32_16x16x32_bf16 v[116:119], v[154:157], v[186:189], v[116:119]
	v_mfma_f32_16x16x32_bf16 v[112:115], v[162:165], v[186:189], v[112:115]
	v_mfma_f32_16x16x32_bf16 v[100:103], v[154:157], v[194:197], v[100:103]
	v_mfma_f32_16x16x32_bf16 v[96:99], v[162:165], v[194:197], v[96:99]
	v_mfma_f32_16x16x32_bf16 v[84:87], v[154:157], v[202:205], v[84:87]
	v_mfma_f32_16x16x32_bf16 v[80:83], v[162:165], v[202:205], v[80:83]
	v_mfma_f32_16x16x32_bf16 v[68:71], v[154:157], v[210:213], v[68:71]
	v_mfma_f32_16x16x32_bf16 v[64:67], v[162:165], v[210:213], v[64:67]
	s_setprio 0
	s_barrier
; #define PG8_LDA(dst, b, h) do { if constexpr (FP8) { _Pragma("unroll") for (int m = 0; m < 4; ++m) dst##8[m] = PG8_LD8(PG8_SA(b, h), aoff, aoff1, m); } \
;         else { _Pragma("unroll") for (int m = 0; m < 4; ++m) _Pragma("unroll") for (int k = 0; k < 2; ++k) dst[m][k] = *(const LAS bf16x8*)(lds + PG8_SA(b, h) + (k ? aoff1 : aoff) + m * 2048); } } while (0)
; #define PG8_WAIT_V(n) asm volatile("s_waitcnt vmcnt(" #n ")" ::: "memory")
; #define PG8_WAIT_L(n) asm volatile("s_waitcnt lgkmcnt(" #n ")" ::: "memory")
; #define PG8_BAR __builtin_amdgcn_s_barrier()
; #define PG8_SCHED __builtin_amdgcn_sched_barrier(0)
; #define PG8_S4 do { PG8_STAGE(PG8_SB(1, 0), b3, voffB); PG8_STAGE(PG8_SB(1, 1), b3 + hstepB, voffB); PG8_STAGE(PG8_SA(1, 0), a3, voffA); } while (0)
; template <class Epi, class SchedT, bool ALIGN_EPI, bool SP2, bool FP8 = false>
; __device__ __forceinline__ void gemm_phase(LAS unsigned char* lds, const Gemm g, const SchedT& S, const Epi& E, const int wid) {
;     ...
;             PG8_LDA(At, 1, 1); PG8_S4;
;             PG8_WAIT_V(8); PG8_WAIT_L(0); PG8_BAR; PG8_MMAP(1, 1, 1); PG8_BAR; PG8_SCHED;
	v_mov_b32_e32 v144, v169
	s_add_i32 s16, s16, s86
	v_lshl_add_u64 v[166:167], s[52:53], 0, v[144:145]
	v_lshl_add_u64 v[166:167], v[166:167], 0, s[6:7]
	s_mov_b32 m0, s16
	v_mov_b32_e32 v144, v171
	global_load_lds_dwordx4 v[166:167], off
	s_add_i32 m0, s16, 0x2000
	s_nop 0
	v_lshl_add_u64 v[166:167], s[52:53], 0, v[144:145]
	s_add_u32 s52, s52, 0x40080
	v_lshl_add_u64 v[166:167], v[166:167], 0, s[6:7]
	s_addc_u32 s53, s53, 0
	v_mov_b32_e32 v144, v169
	s_add_i32 s16, s17, s86
	global_load_lds_dwordx4 v[166:167], off
	s_mov_b32 m0, s16
	s_nop 0
	global_load_lds_dwordx4 v144, s[52:53]
	v_mov_b32_e32 v144, v171
	s_add_i32 m0, s16, 0x2000
	s_nop 0
	global_load_lds_dwordx4 v144, s[52:53]
	v_mov_b32_e32 v144, v168
	s_mov_b32 m0, s92
	v_lshl_add_u64 v[166:167], s[50:51], 0, v[144:145]
	v_lshl_add_u64 v[166:167], v[166:167], 0, s[6:7]
	v_mov_b32_e32 v144, v170
	global_load_lds_dwordx4 v[166:167], off
	s_mov_b32 m0, s93
	v_lshl_add_u64 v[166:167], s[50:51], 0, v[144:145]
	v_lshl_add_u64 v[166:167], v[166:167], 0, s[6:7]
	global_load_lds_dwordx4 v[166:167], off
	ds_read_b128 v[182:185], v177 offset:49152
	ds_read_b128 v[186:189], v177 offset:50176
	ds_read_b128 v[190:193], v177 offset:51200
	ds_read_b128 v[194:197], v177 offset:52224
	ds_read_b128 v[198:201], v177 offset:53248
	ds_read_b128 v[202:205], v177 offset:54272
	ds_read_b128 v[206:209], v177 offset:55296
	ds_read_b128 v[210:213], v177 offset:56320
	s_waitcnt vmcnt(8)
	s_waitcnt lgkmcnt(0)
	s_barrier
	s_setprio 1
	s_waitcnt lgkmcnt(0)
	v_mfma_f32_16x16x32_bf16 v[60:63], v[128:131], v[182:185], v[60:63]
	v_mfma_f32_16x16x32_bf16 v[56:59], v[136:139], v[182:185], v[56:59]
	v_mfma_f32_16x16x32_bf16 v[44:47], v[128:131], v[190:193], v[44:47]
	v_mfma_f32_16x16x32_bf16 v[40:43], v[136:139], v[190:193], v[40:43]
	v_mfma_f32_16x16x32_bf16 v[28:31], v[128:131], v[198:201], v[28:31]
	v_mfma_f32_16x16x32_bf16 v[24:27], v[136:139], v[198:201], v[24:27]
	v_mfma_f32_16x16x32_bf16 v[12:15], v[128:131], v[206:209], v[12:15]
	v_mfma_f32_16x16x32_bf16 v[8:11], v[136:139], v[206:209], v[8:11]
	v_mfma_f32_16x16x32_bf16 v[60:63], v[132:135], v[186:189], v[60:63]
	v_mfma_f32_16x16x32_bf16 v[56:59], v[140:143], v[186:189], v[56:59]
	v_mfma_f32_16x16x32_bf16 v[44:47], v[132:135], v[194:197], v[44:47]
	v_mfma_f32_16x16x32_bf16 v[40:43], v[140:143], v[194:197], v[40:43]
	v_mfma_f32_16x16x32_bf16 v[28:31], v[132:135], v[202:205], v[28:31]
	v_mfma_f32_16x16x32_bf16 v[24:27], v[140:143], v[202:205], v[24:27]
	v_mfma_f32_16x16x32_bf16 v[12:15], v[132:135], v[210:213], v[12:15]
	v_mfma_f32_16x16x32_bf16 v[8:11], v[140:143], v[210:213], v[8:11]
	s_setprio 0
	s_setprio 1
	v_mfma_f32_16x16x32_bf16 v[52:55], v[150:153], v[182:185], v[52:55]
	v_mfma_f32_16x16x32_bf16 v[48:51], v[158:161], v[182:185], v[48:51]
	v_mfma_f32_16x16x32_bf16 v[36:39], v[150:153], v[190:193], v[36:39]
	v_mfma_f32_16x16x32_bf16 v[32:35], v[158:161], v[190:193], v[32:35]
	v_mfma_f32_16x16x32_bf16 v[20:23], v[150:153], v[198:201], v[20:23]
	v_mfma_f32_16x16x32_bf16 v[16:19], v[158:161], v[198:201], v[16:19]
	v_mfma_f32_16x16x32_bf16 v[4:7], v[150:153], v[206:209], v[4:7]
	v_mfma_f32_16x16x32_bf16 v[0:3], v[158:161], v[206:209], v[0:3]
	v_mfma_f32_16x16x32_bf16 v[52:55], v[154:157], v[186:189], v[52:55]
	v_mfma_f32_16x16x32_bf16 v[48:51], v[162:165], v[186:189], v[48:51]
	v_mfma_f32_16x16x32_bf16 v[36:39], v[154:157], v[194:197], v[36:39]
	v_mfma_f32_16x16x32_bf16 v[32:35], v[162:165], v[194:197], v[32:35]
	v_mfma_f32_16x16x32_bf16 v[20:23], v[154:157], v[202:205], v[20:23]
	v_mfma_f32_16x16x32_bf16 v[16:19], v[162:165], v[202:205], v[16:19]
	v_mfma_f32_16x16x32_bf16 v[4:7], v[154:157], v[210:213], v[4:7]
	v_mfma_f32_16x16x32_bf16 v[0:3], v[162:165], v[210:213], v[0:3]
	s_setprio 0
	s_barrier
	s_add_u32 s48, s48, 0x100
	s_addc_u32 s49, s49, 0
	s_add_u32 s30, s30, 0x100
	s_addc_u32 s31, s31, 0
	s_cmp_ge_i32 s35, s20
	s_mov_b32 s34, s35
	s_cbranch_scc0 .LBB0_899
	s_branch .LBB0_894

; #define PG8_LDA(dst, b, h) do { if constexpr (FP8) { _Pragma("unroll") for (int m = 0; m < 4; ++m) dst##8[m] = PG8_LD8(PG8_SA(b, h), aoff, aoff1, m); } \
;         else { _Pragma("unroll") for (int m = 0; m < 4; ++m) _Pragma("unroll") for (int k = 0; k < 2; ++k) dst[m][k] = *(const LAS bf16x8*)(lds + PG8_SA(b, h) + (k ? aoff1 : aoff) + m * 2048); } } while (0)
; #define PG8_LDB(dst, b, h) do { if constexpr (FP8) { dst##8[0] = PG8_LD8(PG8_SB(b, h), boff, boff1, 0); dst##8[1] = PG8_LD8(PG8_SB(b, h), boff, boff1, 1); } \
;         else { _Pragma("unroll") for (int n = 0; n < 2; ++n) _Pragma("unroll") for (int k = 0; k < 2; ++k) dst[n][k] = *(const LAS bf16x8*)(lds + PG8_SB(b, h) + (k ? boff1 : boff) + n * 2048); } } while (0)
; #define PG8_WAIT_V(n) asm volatile("s_waitcnt vmcnt(" #n ")" ::: "memory")
; #define PG8_WAIT_L(n) asm volatile("s_waitcnt lgkmcnt(" #n ")" ::: "memory")
; #define PG8_BAR __builtin_amdgcn_s_barrier()
; #define PG8_SCHED __builtin_amdgcn_sched_barrier(0)
; #define PG8_S1 PG8_STAGE(PG8_SA(1, 1), a1 + hstepA, voffA)
; #define PG8_S2 do { PG8_STAGE(PG8_SB(0, 0), b2, voffB); PG8_STAGE(PG8_SB(0, 1), b2 + hstepB, voffB); PG8_STAGE(PG8_SA(0, 0), a2, voffA); } while (0)
; template <class Epi, class SchedT, bool ALIGN_EPI, bool SP2, bool FP8 = false>
; __device__ __forceinline__ void gemm_phase(LAS unsigned char* lds, const Gemm g, const SchedT& S, const Epi& E, const int wid) {
;     ...
;             const bool last = (t == nt - 2);
;             const char* a1 = cA + (size_t)(t + 1) * kstep;
;             const char* a2 = last ? nA : cA + (size_t)(t + 2) * kstep; const char* b2 = last ? nB : cB + (size_t)(t + 2) * kstep;
;             const char* a3 = a2 + kstep; const char* b3 = b2 + kstep;
;             if constexpr (SP2) {
;     ...
;             PG8_LDB(B0, 0, 0); PG8_LDB(B1, 0, 1); PG8_SCHED; PG8_LDA(At, 0, 0); PG8_S1;
;             PG8_WAIT_V(8); PG8_WAIT_L(0); PG8_BAR; PG8_MMAP(0, 0, 0); PG8_BAR; PG8_SCHED;
;             PG8_LDA(At, 0, 1); PG8_S2;
;             PG8_WAIT_V(8); PG8_WAIT_L(0); PG8_BAR; PG8_MMAP(1, 0, 1); PG8_BAR; PG8_SCHED;
.LBB0_970:
	s_add_i32 s48, s34, 2
	s_add_u32 s16, s24, 0xfff00080
	s_addc_u32 s17, s25, -1
	s_cmp_eq_u32 s45, s34
	s_cselect_b32 s34, s15, s16
	s_cselect_b32 s35, s13, s17
	s_cselect_b32 s39, s27, s47
	s_cselect_b32 s38, s31, s46
	v_mov_b32_e32 v128, v172
	s_add_i32 m0, s87, 0xc000
	s_nop 0
	global_load_lds_dwordx4 v128, s[24:25]
	v_mov_b32_e32 v128, v173
	s_add_i32 m0, s87, 0xe000
	s_nop 0
	global_load_lds_dwordx4 v128, s[24:25]
	ds_read_b128 v[134:137], v175
	ds_read_b128 v[138:141], v175 offset:1024
	ds_read_b128 v[142:145], v176
	ds_read_b128 v[146:149], v176 offset:1024
	ds_read_b128 v[150:153], v177
	ds_read_b128 v[154:157], v177 offset:1024
	ds_read_b128 v[158:161], v178
	ds_read_b128 v[162:165], v178 offset:1024
	ds_read_b128 v[166:169], v179
	ds_read_b128 v[184:187], v179 offset:1024
	ds_read_b128 v[188:191], v179 offset:2048
	ds_read_b128 v[192:195], v179 offset:3072
	ds_read_b128 v[196:199], v179 offset:4096
	ds_read_b128 v[200:203], v179 offset:5120
	ds_read_b128 v[204:207], v179 offset:6144
	ds_read_b128 v[208:211], v179 offset:7168
	s_waitcnt vmcnt(8)
	s_waitcnt lgkmcnt(0)
	s_barrier
	s_setprio 1
	s_waitcnt lgkmcnt(0)
	v_mfma_f32_16x16x32_bf16 v[124:127], v[134:137], v[166:169], v[124:127]
	v_mfma_f32_16x16x32_bf16 v[120:123], v[142:145], v[166:169], v[120:123]
	v_mfma_f32_16x16x32_bf16 v[108:111], v[134:137], v[188:191], v[108:111]
	v_mfma_f32_16x16x32_bf16 v[104:107], v[142:145], v[188:191], v[104:107]
	v_mfma_f32_16x16x32_bf16 v[92:95], v[134:137], v[196:199], v[92:95]
	v_mfma_f32_16x16x32_bf16 v[88:91], v[142:145], v[196:199], v[88:91]
	v_mfma_f32_16x16x32_bf16 v[76:79], v[134:137], v[204:207], v[76:79]
	v_mfma_f32_16x16x32_bf16 v[72:75], v[142:145], v[204:207], v[72:75]
	v_mfma_f32_16x16x32_bf16 v[124:127], v[138:141], v[184:187], v[124:127]
	v_mfma_f32_16x16x32_bf16 v[120:123], v[146:149], v[184:187], v[120:123]
	v_mfma_f32_16x16x32_bf16 v[108:111], v[138:141], v[192:195], v[108:111]
	v_mfma_f32_16x16x32_bf16 v[104:107], v[146:149], v[192:195], v[104:107]
	v_mfma_f32_16x16x32_bf16 v[92:95], v[138:141], v[200:203], v[92:95]
	v_mfma_f32_16x16x32_bf16 v[88:91], v[146:149], v[200:203], v[88:91]
	v_mfma_f32_16x16x32_bf16 v[76:79], v[138:141], v[208:211], v[76:79]
	v_mfma_f32_16x16x32_bf16 v[72:75], v[146:149], v[208:211], v[72:75]
	s_setprio 0
	s_setprio 1
	v_mfma_f32_16x16x32_bf16 v[116:119], v[150:153], v[166:169], v[116:119]
	v_mfma_f32_16x16x32_bf16 v[112:115], v[158:161], v[166:169], v[112:115]
	v_mfma_f32_16x16x32_bf16 v[100:103], v[150:153], v[188:191], v[100:103]
	v_mfma_f32_16x16x32_bf16 v[96:99], v[158:161], v[188:191], v[96:99]
	v_mfma_f32_16x16x32_bf16 v[84:87], v[150:153], v[196:199], v[84:87]
	v_mfma_f32_16x16x32_bf16 v[80:83], v[158:161], v[196:199], v[80:83]
	v_mfma_f32_16x16x32_bf16 v[68:71], v[150:153], v[204:207], v[68:71]
	v_mfma_f32_16x16x32_bf16 v[64:67], v[158:161], v[204:207], v[64:67]
	v_mfma_f32_16x16x32_bf16 v[116:119], v[154:157], v[184:187], v[116:119]
	v_mfma_f32_16x16x32_bf16 v[112:115], v[162:165], v[184:187], v[112:115]
	v_mfma_f32_16x16x32_bf16 v[100:103], v[154:157], v[192:195], v[100:103]
	v_mfma_f32_16x16x32_bf16 v[96:99], v[162:165], v[192:195], v[96:99]
	v_mfma_f32_16x16x32_bf16 v[84:87], v[154:157], v[200:203], v[84:87]
	v_mfma_f32_16x16x32_bf16 v[80:83], v[162:165], v[200:203], v[80:83]
	v_mfma_f32_16x16x32_bf16 v[68:71], v[154:157], v[208:211], v[68:71]
	v_mfma_f32_16x16x32_bf16 v[64:67], v[162:165], v[208:211], v[64:67]
	s_setprio 0
	s_barrier
	v_mov_b32_e32 v128, v172
	s_add_i32 s16, s94, s86
	s_mov_b32 m0, s16
	s_nop 0
	global_load_lds_dwordx4 v128, s[38:39]
	v_mov_b32_e32 v128, v173
	s_add_i32 m0, s16, 0x2000
	s_add_u32 s50, s38, 0x100000
	global_load_lds_dwordx4 v128, s[38:39]
	s_addc_u32 s51, s39, 0
	v_mov_b32_e32 v128, v172
	s_add_i32 s16, s95, s86
	s_mov_b32 m0, s16
	s_nop 0
	global_load_lds_dwordx4 v128, s[50:51]
	v_mov_b32_e32 v128, v173
	s_add_i32 m0, s16, 0x2000
	s_nop 0
	global_load_lds_dwordx4 v128, s[50:51]
	v_mov_b32_e32 v128, v172
	s_mov_b32 m0, s87
	s_nop 0
	global_load_lds_dwordx4 v128, s[34:35]
	v_mov_b32_e32 v128, v173
	s_mov_b32 m0, s88
	s_nop 0
	global_load_lds_dwordx4 v128, s[34:35]
	ds_read_b128 v[166:169], v179 offset:16384
	ds_read_b128 v[184:187], v179 offset:17408
	ds_read_b128 v[188:191], v179 offset:18432
	ds_read_b128 v[192:195], v179 offset:19456
	ds_read_b128 v[196:199], v179 offset:20480
	ds_read_b128 v[200:203], v179 offset:21504
	ds_read_b128 v[204:207], v179 offset:22528
	ds_read_b128 v[208:211], v179 offset:23552
	s_waitcnt vmcnt(8)
	s_waitcnt lgkmcnt(0)
	s_barrier
; #define PG8_LDA(dst, b, h) do { if constexpr (FP8) { _Pragma("unroll") for (int m = 0; m < 4; ++m) dst##8[m] = PG8_LD8(PG8_SA(b, h), aoff, aoff1, m); } \
;         else { _Pragma("unroll") for (int m = 0; m < 4; ++m) _Pragma("unroll") for (int k = 0; k < 2; ++k) dst[m][k] = *(const LAS bf16x8*)(lds + PG8_SA(b, h) + (k ? aoff1 : aoff) + m * 2048); } } while (0)
; #define PG8_LDB(dst, b, h) do { if constexpr (FP8) { dst##8[0] = PG8_LD8(PG8_SB(b, h), boff, boff1, 0); dst##8[1] = PG8_LD8(PG8_SB(b, h), boff, boff1, 1); } \
;         else { _Pragma("unroll") for (int n = 0; n < 2; ++n) _Pragma("unroll") for (int k = 0; k < 2; ++k) dst[n][k] = *(const LAS bf16x8*)(lds + PG8_SB(b, h) + (k ? boff1 : boff) + n * 2048); } } while (0)
; #define PG8_WAIT_V(n) asm volatile("s_waitcnt vmcnt(" #n ")" ::: "memory")
; #define PG8_WAIT_L(n) asm volatile("s_waitcnt lgkmcnt(" #n ")" ::: "memory")
; #define PG8_BAR __builtin_amdgcn_s_barrier()
; #define PG8_SCHED __builtin_amdgcn_sched_barrier(0)
; #define PG8_S1 PG8_STAGE(PG8_SA(1, 1), a1 + hstepA, voffA)
; #define PG8_S2 do { PG8_STAGE(PG8_SB(0, 0), b2, voffB); PG8_STAGE(PG8_SB(0, 1), b2 + hstepB, voffB); PG8_STAGE(PG8_SA(0, 0), a2, voffA); } while (0)
; #define PG8_S3 PG8_STAGE(PG8_SA(0, 1), a2 + hstepA, voffA)
; #define PG8_S4 do { PG8_STAGE(PG8_SB(1, 0), b3, voffB); PG8_STAGE(PG8_SB(1, 1), b3 + hstepB, voffB); PG8_STAGE(PG8_SA(1, 0), a3, voffA); } while (0)
; template <class Epi, class SchedT, bool ALIGN_EPI, bool SP2, bool FP8 = false>
; __device__ __forceinline__ void gemm_phase(LAS unsigned char* lds, const Gemm g, const SchedT& S, const Epi& E, const int wid) {
;     ...
;             PG8_LDB(B0, 0, 0); PG8_LDB(B1, 0, 1); PG8_SCHED; PG8_LDA(At, 0, 0); PG8_S1;
;             PG8_WAIT_V(8); PG8_WAIT_L(0); PG8_BAR; PG8_MMAP(0, 0, 0); PG8_BAR; PG8_SCHED;
;             PG8_LDA(At, 0, 1); PG8_S2;
;             PG8_WAIT_V(8); PG8_WAIT_L(0); PG8_BAR; PG8_MMAP(1, 0, 1); PG8_BAR; PG8_SCHED;
;             PG8_LDB(B0, 1, 0); PG8_LDB(B1, 1, 1); PG8_SCHED; PG8_LDA(At, 1, 0); PG8_S3;
;             PG8_WAIT_V(8); PG8_WAIT_L(0); PG8_BAR; PG8_MMAP(0, 1, 0); PG8_BAR; PG8_SCHED;
;             PG8_LDA(At, 1, 1); PG8_S4;
;             PG8_WAIT_V(8); PG8_WAIT_L(0); PG8_BAR; PG8_MMAP(1, 1, 1); PG8_BAR; PG8_SCHED;
	s_setprio 1
	s_waitcnt lgkmcnt(0)
	v_mfma_f32_16x16x32_bf16 v[60:63], v[134:137], v[166:169], v[60:63]
	v_mfma_f32_16x16x32_bf16 v[56:59], v[142:145], v[166:169], v[56:59]
	v_mfma_f32_16x16x32_bf16 v[44:47], v[134:137], v[188:191], v[44:47]
	v_mfma_f32_16x16x32_bf16 v[40:43], v[142:145], v[188:191], v[40:43]
	v_mfma_f32_16x16x32_bf16 v[28:31], v[134:137], v[196:199], v[28:31]
	v_mfma_f32_16x16x32_bf16 v[24:27], v[142:145], v[196:199], v[24:27]
	v_mfma_f32_16x16x32_bf16 v[12:15], v[134:137], v[204:207], v[12:15]
	v_mfma_f32_16x16x32_bf16 v[8:11], v[142:145], v[204:207], v[8:11]
	v_mfma_f32_16x16x32_bf16 v[60:63], v[138:141], v[184:187], v[60:63]
	v_mfma_f32_16x16x32_bf16 v[56:59], v[146:149], v[184:187], v[56:59]
	v_mfma_f32_16x16x32_bf16 v[44:47], v[138:141], v[192:195], v[44:47]
	v_mfma_f32_16x16x32_bf16 v[40:43], v[146:149], v[192:195], v[40:43]
	v_mfma_f32_16x16x32_bf16 v[28:31], v[138:141], v[200:203], v[28:31]
	v_mfma_f32_16x16x32_bf16 v[24:27], v[146:149], v[200:203], v[24:27]
	v_mfma_f32_16x16x32_bf16 v[12:15], v[138:141], v[208:211], v[12:15]
	v_mfma_f32_16x16x32_bf16 v[8:11], v[146:149], v[208:211], v[8:11]
	s_setprio 0
	s_setprio 1
	v_mfma_f32_16x16x32_bf16 v[52:55], v[150:153], v[166:169], v[52:55]
	v_mfma_f32_16x16x32_bf16 v[48:51], v[158:161], v[166:169], v[48:51]
	v_mfma_f32_16x16x32_bf16 v[36:39], v[150:153], v[188:191], v[36:39]
	v_mfma_f32_16x16x32_bf16 v[32:35], v[158:161], v[188:191], v[32:35]
	v_mfma_f32_16x16x32_bf16 v[20:23], v[150:153], v[196:199], v[20:23]
	v_mfma_f32_16x16x32_bf16 v[16:19], v[158:161], v[196:199], v[16:19]
	v_mfma_f32_16x16x32_bf16 v[4:7], v[150:153], v[204:207], v[4:7]
	v_mfma_f32_16x16x32_bf16 v[0:3], v[158:161], v[204:207], v[0:3]
	v_mfma_f32_16x16x32_bf16 v[52:55], v[154:157], v[184:187], v[52:55]
	v_mfma_f32_16x16x32_bf16 v[48:51], v[162:165], v[184:187], v[48:51]
	v_mfma_f32_16x16x32_bf16 v[36:39], v[154:157], v[192:195], v[36:39]
	v_mfma_f32_16x16x32_bf16 v[32:35], v[162:165], v[192:195], v[32:35]
	v_mfma_f32_16x16x32_bf16 v[20:23], v[154:157], v[200:203], v[20:23]
	v_mfma_f32_16x16x32_bf16 v[16:19], v[162:165], v[200:203], v[16:19]
	v_mfma_f32_16x16x32_bf16 v[4:7], v[154:157], v[208:211], v[4:7]
	v_mfma_f32_16x16x32_bf16 v[0:3], v[162:165], v[208:211], v[0:3]
	s_setprio 0
	s_barrier
	s_add_i32 s16, 0, 0x18000
	s_add_i32 s17, 0, 0x1c000
	s_add_u32 s50, s34, 0x100000
	s_mov_b32 m0, s89
	s_addc_u32 s51, s35, 0
	s_nop 0
	global_load_lds_dwordx4 v172, s[50:51]
	s_mov_b32 m0, s90
	s_nop 0
	global_load_lds_dwordx4 v173, s[50:51]
	v_add_u32_e32 v128, s16, v174
	ds_read_b128 v[134:137], v128
	ds_read_b128 v[138:141], v128 offset:1024
	ds_read_b128 v[142:145], v180
	ds_read_b128 v[146:149], v180 offset:1024
	v_add_u32_e32 v128, s17, v174
	ds_read_b128 v[150:153], v128
	ds_read_b128 v[154:157], v128 offset:1024
	ds_read_b128 v[158:161], v181
	ds_read_b128 v[162:165], v181 offset:1024
	ds_read_b128 v[166:169], v179 offset:32768
	ds_read_b128 v[184:187], v179 offset:33792
	ds_read_b128 v[188:191], v179 offset:34816
	ds_read_b128 v[192:195], v179 offset:35840
	ds_read_b128 v[196:199], v179 offset:36864
	ds_read_b128 v[200:203], v179 offset:37888
	ds_read_b128 v[204:207], v179 offset:38912
	ds_read_b128 v[208:211], v179 offset:39936
	s_waitcnt vmcnt(8)
	s_waitcnt lgkmcnt(0)
	s_barrier
	s_setprio 1
	s_waitcnt lgkmcnt(0)
	v_mfma_f32_16x16x32_bf16 v[124:127], v[134:137], v[166:169], v[124:127]
	v_mfma_f32_16x16x32_bf16 v[120:123], v[142:145], v[166:169], v[120:123]
	v_mfma_f32_16x16x32_bf16 v[108:111], v[134:137], v[188:191], v[108:111]
	v_mfma_f32_16x16x32_bf16 v[104:107], v[142:145], v[188:191], v[104:107]
	v_mfma_f32_16x16x32_bf16 v[92:95], v[134:137], v[196:199], v[92:95]
	v_mfma_f32_16x16x32_bf16 v[88:91], v[142:145], v[196:199], v[88:91]
	v_mfma_f32_16x16x32_bf16 v[76:79], v[134:137], v[204:207], v[76:79]
	v_mfma_f32_16x16x32_bf16 v[72:75], v[142:145], v[204:207], v[72:75]
	v_mfma_f32_16x16x32_bf16 v[124:127], v[138:141], v[184:187], v[124:127]
	v_mfma_f32_16x16x32_bf16 v[120:123], v[146:149], v[184:187], v[120:123]
	v_mfma_f32_16x16x32_bf16 v[108:111], v[138:141], v[192:195], v[108:111]
	v_mfma_f32_16x16x32_bf16 v[104:107], v[146:149], v[192:195], v[104:107]
	v_mfma_f32_16x16x32_bf16 v[92:95], v[138:141], v[200:203], v[92:95]
	v_mfma_f32_16x16x32_bf16 v[88:91], v[146:149], v[200:203], v[88:91]
	v_mfma_f32_16x16x32_bf16 v[76:79], v[138:141], v[208:211], v[76:79]
	v_mfma_f32_16x16x32_bf16 v[72:75], v[146:149], v[208:211], v[72:75]
	s_setprio 0
	s_setprio 1
	v_mfma_f32_16x16x32_bf16 v[116:119], v[150:153], v[166:169], v[116:119]
	v_mfma_f32_16x16x32_bf16 v[112:115], v[158:161], v[166:169], v[112:115]
	v_mfma_f32_16x16x32_bf16 v[100:103], v[150:153], v[188:191], v[100:103]
	v_mfma_f32_16x16x32_bf16 v[96:99], v[158:161], v[188:191], v[96:99]
	v_mfma_f32_16x16x32_bf16 v[84:87], v[150:153], v[196:199], v[84:87]
	v_mfma_f32_16x16x32_bf16 v[80:83], v[158:161], v[196:199], v[80:83]
	v_mfma_f32_16x16x32_bf16 v[68:71], v[150:153], v[204:207], v[68:71]
	v_mfma_f32_16x16x32_bf16 v[64:67], v[158:161], v[204:207], v[64:67]
	v_mfma_f32_16x16x32_bf16 v[116:119], v[154:157], v[184:187], v[116:119]
	v_mfma_f32_16x16x32_bf16 v[112:115], v[162:165], v[184:187], v[112:115]
	v_mfma_f32_16x16x32_bf16 v[100:103], v[154:157], v[192:195], v[100:103]
	v_mfma_f32_16x16x32_bf16 v[96:99], v[162:165], v[192:195], v[96:99]
	v_mfma_f32_16x16x32_bf16 v[84:87], v[154:157], v[200:203], v[84:87]
	v_mfma_f32_16x16x32_bf16 v[80:83], v[162:165], v[200:203], v[80:83]
	v_mfma_f32_16x16x32_bf16 v[68:71], v[154:157], v[208:211], v[68:71]
	v_mfma_f32_16x16x32_bf16 v[64:67], v[162:165], v[208:211], v[64:67]
	s_setprio 0
	s_barrier
; #define PG8_LDA(dst, b, h) do { if constexpr (FP8) { _Pragma("unroll") for (int m = 0; m < 4; ++m) dst##8[m] = PG8_LD8(PG8_SA(b, h), aoff, aoff1, m); } \
;         else { _Pragma("unroll") for (int m = 0; m < 4; ++m) _Pragma("unroll") for (int k = 0; k < 2; ++k) dst[m][k] = *(const LAS bf16x8*)(lds + PG8_SA(b, h) + (k ? aoff1 : aoff) + m * 2048); } } while (0)
; #define PG8_WAIT_V(n) asm volatile("s_waitcnt vmcnt(" #n ")" ::: "memory")
; #define PG8_WAIT_L(n) asm volatile("s_waitcnt lgkmcnt(" #n ")" ::: "memory")
; #define PG8_BAR __builtin_amdgcn_s_barrier()
; #define PG8_SCHED __builtin_amdgcn_sched_barrier(0)
; #define PG8_S4 do { PG8_STAGE(PG8_SB(1, 0), b3, voffB); PG8_STAGE(PG8_SB(1, 1), b3 + hstepB, voffB); PG8_STAGE(PG8_SA(1, 0), a3, voffA); } while (0)
; template <class Epi, class SchedT, bool ALIGN_EPI, bool SP2, bool FP8 = false>
; __device__ __forceinline__ void gemm_phase(LAS unsigned char* lds, const Gemm g, const SchedT& S, const Epi& E, const int wid) {
;     ...
;             PG8_LDA(At, 1, 1); PG8_S4;
;             PG8_WAIT_V(8); PG8_WAIT_L(0); PG8_BAR; PG8_MMAP(1, 1, 1); PG8_BAR; PG8_SCHED;
	v_mov_b32_e32 v128, v172
	s_add_i32 s16, s16, s86
	v_lshl_add_u64 v[170:171], s[38:39], 0, v[128:129]
	v_lshl_add_u64 v[170:171], v[170:171], 0, s[8:9]
	s_mov_b32 m0, s16
	v_mov_b32_e32 v128, v173
	global_load_lds_dwordx4 v[170:171], off
	s_add_i32 m0, s16, 0x2000
	s_nop 0
	v_lshl_add_u64 v[170:171], s[38:39], 0, v[128:129]
	s_add_u32 s38, s38, 0x100080
	v_lshl_add_u64 v[170:171], v[170:171], 0, s[8:9]
	s_addc_u32 s39, s39, 0
	v_mov_b32_e32 v128, v172
	s_add_i32 s16, s17, s86
	global_load_lds_dwordx4 v[170:171], off
	s_mov_b32 m0, s16
	s_nop 0
	global_load_lds_dwordx4 v128, s[38:39]
	v_mov_b32_e32 v128, v173
	s_add_i32 m0, s16, 0x2000
	s_nop 0
	global_load_lds_dwordx4 v128, s[38:39]
	v_mov_b32_e32 v128, v172
	s_mov_b32 m0, s92
	v_lshl_add_u64 v[170:171], s[34:35], 0, v[128:129]
	v_lshl_add_u64 v[170:171], v[170:171], 0, s[8:9]
	v_mov_b32_e32 v128, v173
	global_load_lds_dwordx4 v[170:171], off
	s_mov_b32 m0, s93
	v_lshl_add_u64 v[170:171], s[34:35], 0, v[128:129]
	v_lshl_add_u64 v[170:171], v[170:171], 0, s[8:9]
	global_load_lds_dwordx4 v[170:171], off
	ds_read_b128 v[166:169], v179 offset:49152
	ds_read_b128 v[184:187], v179 offset:50176
	ds_read_b128 v[188:191], v179 offset:51200
	ds_read_b128 v[192:195], v179 offset:52224
	ds_read_b128 v[196:199], v179 offset:53248
	ds_read_b128 v[200:203], v179 offset:54272
	ds_read_b128 v[204:207], v179 offset:55296
	ds_read_b128 v[208:211], v179 offset:56320
	s_waitcnt vmcnt(8)
	s_waitcnt lgkmcnt(0)
	s_barrier
	s_setprio 1
	s_waitcnt lgkmcnt(0)
	v_mfma_f32_16x16x32_bf16 v[60:63], v[134:137], v[166:169], v[60:63]
	v_mfma_f32_16x16x32_bf16 v[56:59], v[142:145], v[166:169], v[56:59]
	v_mfma_f32_16x16x32_bf16 v[44:47], v[134:137], v[188:191], v[44:47]
	v_mfma_f32_16x16x32_bf16 v[40:43], v[142:145], v[188:191], v[40:43]
	v_mfma_f32_16x16x32_bf16 v[28:31], v[134:137], v[196:199], v[28:31]
	v_mfma_f32_16x16x32_bf16 v[24:27], v[142:145], v[196:199], v[24:27]
	v_mfma_f32_16x16x32_bf16 v[12:15], v[134:137], v[204:207], v[12:15]
	v_mfma_f32_16x16x32_bf16 v[8:11], v[142:145], v[204:207], v[8:11]
	v_mfma_f32_16x16x32_bf16 v[60:63], v[138:141], v[184:187], v[60:63]
	v_mfma_f32_16x16x32_bf16 v[56:59], v[146:149], v[184:187], v[56:59]
	v_mfma_f32_16x16x32_bf16 v[44:47], v[138:141], v[192:195], v[44:47]
	v_mfma_f32_16x16x32_bf16 v[40:43], v[146:149], v[192:195], v[40:43]
	v_mfma_f32_16x16x32_bf16 v[28:31], v[138:141], v[200:203], v[28:31]
	v_mfma_f32_16x16x32_bf16 v[24:27], v[146:149], v[200:203], v[24:27]
	v_mfma_f32_16x16x32_bf16 v[12:15], v[138:141], v[208:211], v[12:15]
	v_mfma_f32_16x16x32_bf16 v[8:11], v[146:149], v[208:211], v[8:11]
	s_setprio 0
	s_setprio 1
	v_mfma_f32_16x16x32_bf16 v[52:55], v[150:153], v[166:169], v[52:55]
	v_mfma_f32_16x16x32_bf16 v[48:51], v[158:161], v[166:169], v[48:51]
	v_mfma_f32_16x16x32_bf16 v[36:39], v[150:153], v[188:191], v[36:39]
	v_mfma_f32_16x16x32_bf16 v[32:35], v[158:161], v[188:191], v[32:35]
	v_mfma_f32_16x16x32_bf16 v[20:23], v[150:153], v[196:199], v[20:23]
	v_mfma_f32_16x16x32_bf16 v[16:19], v[158:161], v[196:199], v[16:19]
	v_mfma_f32_16x16x32_bf16 v[4:7], v[150:153], v[204:207], v[4:7]
	v_mfma_f32_16x16x32_bf16 v[0:3], v[158:161], v[204:207], v[0:3]
	v_mfma_f32_16x16x32_bf16 v[52:55], v[154:157], v[184:187], v[52:55]
	v_mfma_f32_16x16x32_bf16 v[48:51], v[162:165], v[184:187], v[48:51]
	v_mfma_f32_16x16x32_bf16 v[36:39], v[154:157], v[192:195], v[36:39]
	v_mfma_f32_16x16x32_bf16 v[32:35], v[162:165], v[192:195], v[32:35]
	v_mfma_f32_16x16x32_bf16 v[20:23], v[154:157], v[200:203], v[20:23]
	v_mfma_f32_16x16x32_bf16 v[16:19], v[162:165], v[200:203], v[16:19]
	v_mfma_f32_16x16x32_bf16 v[4:7], v[154:157], v[208:211], v[4:7]
	v_mfma_f32_16x16x32_bf16 v[0:3], v[162:165], v[208:211], v[0:3]
	s_setprio 0
	s_barrier
	s_add_u32 s24, s24, 0x100
	s_addc_u32 s25, s25, 0
	s_add_u32 s46, s46, 0x100
	s_addc_u32 s47, s47, 0
	s_cmp_ge_i32 s48, s30
	s_mov_b32 s34, s48
	s_cbranch_scc0 .LBB0_970
	s_and_b64 vcc, exec, s[96:97]
	s_cbranch_vccz .LBB0_973
